# P2 tile boundary: hipcc's VALU-based wave-uniform test (v_cndmask+v_cmp) replaced by one s_andn2_b64
# baseline (speedup 1.0000x reference)
.Lp2_u217:
	s_andn2_b64 s[10:11], exec, s[8:9]
	s_andn2_b64 vcc, exec, s[8:9]
	s_mov_b64 s[8:9], s[20:21]
	s_cbranch_vccnz .Lp2_u219
	s_ashr_i32 s8, s41, 31
	s_mul_hi_u32 s9, s14, s41
	s_mul_i32 s8, s14, s8
	s_add_i32 s8, s9, s8
	s_mul_i32 s9, s15, s41
	s_add_i32 s9, s8, s9
	s_mul_i32 s8, s14, s41
	s_add_u32 s8, s24, s8
	s_addc_u32 s9, s5, s9
